# m3 PV stage: A fragments kept in registers, B fragments of each 16-column block prefetched one block ahead (on the v72 base)
# speedup vs baseline: 1.0006x; 1.0006x over previous
.LBB0_448:
	s_or_b64 exec, exec, s[2:3]
	v_bfe_u32 v3, v1, 16, 1
	s_movk_i32 s2, 0x7fff
	v_lshlrev_b32_e32 v2, 3, v4
	v_add3_u32 v1, v1, v3, s2
	ds_write_b16_d16_hi v0, v1 offset:60336
	v_mul_u32_u24_e32 v0, 0x90, v9
	v_lshlrev_b32_e32 v1, 1, v2
	s_waitcnt lgkmcnt(0)
	s_barrier
	v_add3_u32 v12, 0, v0, v1
	ds_read_b128 v[100:103], v10 offset:59904
	ds_read_b128 v[104:107], v10 offset:59968
	ds_read_b128 v[108:111], v10
	ds_read_b128 v[112:115], v10 offset:64
	ds_read_b128 v[14:17], v10 offset:59904
	ds_read_b128 v[0:3], v12 offset:36864
	ds_read_b128 v[18:21], v10 offset:59968
	ds_read_b128 v[4:7], v12 offset:36928
	s_waitcnt lgkmcnt(2)
	v_mfma_f32_16x16x32_bf16 v[0:3], v[14:17], v[0:3], 0
	s_lshl_b32 s2, s4, 2
	s_add_i32 s2, s2, 0
	s_add_i32 s2, s2, 0x19200
	s_waitcnt lgkmcnt(0)
	v_mfma_f32_16x16x32_bf16 v[24:27], v[18:21], v[4:7], v[0:3]
	ds_read_b128 v[28:31], v10
	s_nop 1
	ds_read_b128 v[0:3], v12 offset:57600
	ds_read_b128 v[32:35], v10 offset:64
	ds_read_b128 v[4:7], v12 offset:57664
	s_ashr_i32 s3, s40, 6
	s_waitcnt lgkmcnt(2)
	v_mfma_f32_16x16x32_bf16 v[0:3], v[28:31], v[0:3], 0
	v_readlane_b32 s7, v254, 34
	s_waitcnt lgkmcnt(0)
	v_mfma_f32_16x16x32_bf16 v[36:39], v[32:35], v[4:7], v[0:3]
	s_nop 4
	v_and_b32_e32 v0, 48, v23
	v_add_u32_e32 v4, s2, v0
	v_and_or_b32 v0, v201, 64, v0
	v_lshlrev_b32_e32 v12, 2, v0
	ds_read_b128 v[0:3], v4 offset:512
	ds_read_b128 v[4:7], v4 offset:768
	s_lshl_b32 s2, s3, 4
	s_and_b32 s6, s2, 0xffffffc0
	v_or_b32_e32 v40, s6, v9
	s_waitcnt lgkmcnt(1)
	v_fma_f32 v13, v36, v0, v24
	v_fma_f32 v23, v37, v1, v25
	v_fma_f32 v24, v38, v2, v26
	v_fmac_f32_e32 v27, v39, v3
	v_mad_u64_u32 v[36:37], s[4:5], v40, s84, v[8:9]
	v_mov_b32_e32 v116, v36
	ds_read_b128 v[120:123], v116 offset:20736
	ds_read_b128 v[124:127], v116 offset:20800
	ds_read_b128 v[128:131], v116 offset:41472
	ds_read_b128 v[132:135], v116 offset:41536
	ds_bpermute_b32 v38, v12, v24
	ds_bpermute_b32 v39, v12, v27
	ds_read_b128 v[24:27], v36 offset:18432
	s_waitcnt lgkmcnt(0)
	v_mfma_f32_16x16x32_bf16 v[14:17], v[14:17], v[24:27], 0
	ds_read_b128 v[24:27], v36 offset:18496
	ds_bpermute_b32 v13, v12, v13
	v_max_f32_e32 v4, v4, v4
	s_waitcnt lgkmcnt(1)
	v_mfma_f32_16x16x32_bf16 v[14:17], v[18:21], v[24:27], v[14:17]
	ds_read_b128 v[18:21], v36 offset:39168
	ds_read_b128 v[24:27], v36 offset:39232
	s_waitcnt lgkmcnt(2)
	v_max_f32_e64 v13, |v13|, |v13|
	s_waitcnt lgkmcnt(1)
	v_mfma_f32_16x16x32_bf16 v[18:21], v[28:31], v[18:21], 0
	v_max_f32_e32 v4, v13, v4
	ds_bpermute_b32 v23, v12, v23
	v_lshl_add_u32 v12, v9, 2, s7
	s_waitcnt lgkmcnt(1)
	v_mfma_f32_16x16x32_bf16 v[18:21], v[32:35], v[24:27], v[18:21]
	v_lshl_add_u32 v24, s6, 2, v12
	s_movk_i32 s6, 0x210
	v_mad_u32_u24 v36, v11, s6, v24
	v_max_f32_e32 v5, v5, v5
	v_max_f32_e32 v6, v6, v6
	s_nop 2
	v_fma_f32 v14, v0, v18, v14
	v_div_scale_f32 v13, s[4:5], v4, v4, v14
	v_rcp_f32_e32 v18, v13
	v_max_f32_e32 v7, v7, v7
	v_fmac_f32_e32 v17, v3, v21
	s_or_b32 s2, s2, 48
	v_fma_f32 v25, -v13, v18, 1.0
	v_fmac_f32_e32 v18, v25, v18
	v_div_scale_f32 v25, vcc, v14, v4, v14
	v_mul_f32_e32 v26, v25, v18
	v_fma_f32 v27, -v13, v26, v25
	v_fmac_f32_e32 v26, v27, v18
	v_fma_f32 v13, -v13, v26, v25
	v_div_fmas_f32 v13, v13, v18, v26
	v_div_fixup_f32 v13, v13, v4, v14
	s_waitcnt lgkmcnt(0)
	v_max_f32_e64 v14, |v23|, |v23|
	ds_write_b32 v36, v13
	v_fma_f32 v13, v1, v19, v15
	v_max_f32_e32 v5, v14, v5
	v_div_scale_f32 v14, s[4:5], v5, v5, v13
	v_rcp_f32_e32 v15, v14
	s_nop 0
	v_fma_f32 v18, -v14, v15, 1.0
	v_fmac_f32_e32 v15, v18, v15
	v_div_scale_f32 v18, vcc, v13, v5, v13
	v_mul_f32_e32 v19, v18, v15
	v_fma_f32 v23, -v14, v19, v18
	v_fmac_f32_e32 v19, v23, v15
	v_fma_f32 v14, -v14, v19, v18
	v_div_fmas_f32 v14, v14, v15, v19
	v_div_fixup_f32 v14, v14, v5, v13
	v_mad_u32_u24 v13, v11, s6, s6
	v_add_u32_e32 v23, v24, v13
	v_max_f32_e64 v15, |v38|, |v38|
	ds_write_b32 v23, v14
	v_fma_f32 v14, v2, v20, v16
	v_max_f32_e32 v6, v15, v6
	v_div_scale_f32 v15, s[4:5], v6, v6, v14
	v_rcp_f32_e32 v16, v15
	s_nop 0
	v_fma_f32 v18, -v15, v16, 1.0
	v_fmac_f32_e32 v16, v18, v16
	v_div_scale_f32 v18, vcc, v14, v6, v14
	v_mul_f32_e32 v19, v18, v16
	v_fma_f32 v20, -v15, v19, v18
	v_fmac_f32_e32 v19, v20, v16
	v_fma_f32 v15, -v15, v19, v18
	v_div_fmas_f32 v15, v15, v16, v19
	v_div_fixup_f32 v15, v15, v6, v14
	v_mov_b32_e32 v14, 0x420
	v_mad_u32_u24 v14, v11, s6, v14
	v_add_u32_e32 v37, v24, v14
	ds_write_b32 v37, v15
	v_max_f32_e64 v15, |v39|, |v39|
	v_max_f32_e32 v7, v15, v7
	v_div_scale_f32 v15, s[4:5], v7, v7, v17
	v_rcp_f32_e32 v16, v15
	s_nop 0
	v_fma_f32 v18, -v15, v16, 1.0
	v_fmac_f32_e32 v16, v18, v16
	v_div_scale_f32 v18, vcc, v17, v7, v17
	v_mul_f32_e32 v19, v18, v16
	v_fma_f32 v20, -v15, v19, v18
	v_fmac_f32_e32 v19, v20, v16
	v_fma_f32 v15, -v15, v19, v18
	v_div_fmas_f32 v15, v15, v16, v19
	v_div_fixup_f32 v16, v15, v7, v17
	v_mad_u32_u24 v15, v11, s6, v206
	v_add_u32_e32 v38, v24, v15
	ds_write_b32 v38, v16
	v_or_b32_e32 v16, 16, v40
	v_mad_u64_u32 v[20:21], s[4:5], v16, s84, v[8:9]
	s_waitcnt lgkmcnt(0)
	v_mfma_f32_16x16x32_bf16 v[16:19], v[100:103], v[120:123], 0
	v_mfma_f32_16x16x32_bf16 v[24:27], v[108:111], v[128:131], 0
	v_mfma_f32_16x16x32_bf16 v[16:19], v[104:107], v[124:127], v[16:19]
	v_mfma_f32_16x16x32_bf16 v[24:27], v[112:115], v[132:135], v[24:27]
	ds_read_b128 v[136:139], v116 offset:23040
	ds_read_b128 v[140:143], v116 offset:23104
	ds_read_b128 v[144:147], v116 offset:43776
	ds_read_b128 v[148:151], v116 offset:43840
	s_nop 7
	v_fma_f32 v16, v0, v24, v16
	v_div_scale_f32 v20, s[4:5], v4, v4, v16
	v_rcp_f32_e32 v21, v20
	v_fmac_f32_e32 v19, v3, v27
	v_fma_f32 v24, -v20, v21, 1.0
	v_fmac_f32_e32 v21, v24, v21
	v_div_scale_f32 v24, vcc, v16, v4, v16
	v_mul_f32_e32 v28, v24, v21
	v_fma_f32 v29, -v20, v28, v24
	v_fmac_f32_e32 v28, v29, v21
	v_fma_f32 v20, -v20, v28, v24
	v_div_fmas_f32 v20, v20, v21, v28
	v_div_fixup_f32 v16, v20, v4, v16
	ds_write_b32 v36, v16 offset:64
	v_fma_f32 v16, v1, v25, v17
	v_div_scale_f32 v17, s[4:5], v5, v5, v16
	v_rcp_f32_e32 v20, v17
	s_nop 0
	v_fma_f32 v21, -v17, v20, 1.0
	v_fmac_f32_e32 v20, v21, v20
	v_div_scale_f32 v21, vcc, v16, v5, v16
	v_mul_f32_e32 v24, v21, v20
	v_fma_f32 v25, -v17, v24, v21
	v_fmac_f32_e32 v24, v25, v20
	v_fma_f32 v17, -v17, v24, v21
	v_div_fmas_f32 v17, v17, v20, v24
	v_div_fixup_f32 v16, v17, v5, v16
	ds_write_b32 v23, v16 offset:64
	v_fma_f32 v16, v2, v26, v18
	v_div_scale_f32 v17, s[4:5], v6, v6, v16
	v_rcp_f32_e32 v18, v17
	s_nop 0
	v_fma_f32 v20, -v17, v18, 1.0
	v_fmac_f32_e32 v18, v20, v18
	v_div_scale_f32 v20, vcc, v16, v6, v16
	v_mul_f32_e32 v21, v20, v18
	v_fma_f32 v24, -v17, v21, v20
	v_fmac_f32_e32 v21, v24, v18
	v_fma_f32 v17, -v17, v21, v20
	v_div_fmas_f32 v17, v17, v18, v21
	v_div_fixup_f32 v16, v17, v6, v16
	ds_write_b32 v37, v16 offset:64
	v_div_scale_f32 v16, s[4:5], v7, v7, v19
	v_rcp_f32_e32 v17, v16
	s_nop 0
	v_fma_f32 v18, -v16, v17, 1.0
	v_fmac_f32_e32 v17, v18, v17
	v_div_scale_f32 v18, vcc, v19, v7, v19
	v_mul_f32_e32 v20, v18, v17
	v_fma_f32 v21, -v16, v20, v18
	v_fmac_f32_e32 v20, v21, v17
	v_fma_f32 v16, -v16, v20, v18
	v_div_fmas_f32 v16, v16, v17, v20
	v_div_fixup_f32 v16, v16, v7, v19
	ds_write_b32 v38, v16 offset:64
	v_or_b32_e32 v16, 32, v40
	v_mad_u64_u32 v[20:21], s[4:5], v16, s84, v[8:9]
	v_or_b32_e32 v9, s2, v9
	v_mad_u64_u32 v[8:9], s[4:5], v9, s84, v[8:9]
	s_waitcnt lgkmcnt(0)
	v_mfma_f32_16x16x32_bf16 v[16:19], v[100:103], v[136:139], 0
	v_mfma_f32_16x16x32_bf16 v[24:27], v[108:111], v[144:147], 0
	v_mfma_f32_16x16x32_bf16 v[16:19], v[104:107], v[140:143], v[16:19]
	v_mfma_f32_16x16x32_bf16 v[24:27], v[112:115], v[148:151], v[24:27]
	ds_read_b128 v[120:123], v116 offset:25344
	ds_read_b128 v[124:127], v116 offset:25408
	ds_read_b128 v[128:131], v116 offset:46080
	ds_read_b128 v[132:135], v116 offset:46144
	s_nop 7
	v_fma_f32 v16, v0, v24, v16
	v_div_scale_f32 v20, s[4:5], v4, v4, v16
	v_rcp_f32_e32 v21, v20
	v_fmac_f32_e32 v19, v3, v27
	v_fma_f32 v24, -v20, v21, 1.0
	v_fmac_f32_e32 v21, v24, v21
	v_div_scale_f32 v24, vcc, v16, v4, v16
	v_mul_f32_e32 v28, v24, v21
	v_fma_f32 v29, -v20, v28, v24
	v_fmac_f32_e32 v28, v29, v21
	v_fma_f32 v20, -v20, v28, v24
	v_div_fmas_f32 v20, v20, v21, v28
	v_div_fixup_f32 v16, v20, v4, v16
	ds_write_b32 v36, v16 offset:128
	v_fma_f32 v16, v1, v25, v17
	v_div_scale_f32 v17, s[4:5], v5, v5, v16
	v_rcp_f32_e32 v20, v17
	s_nop 0
	v_fma_f32 v21, -v17, v20, 1.0
	v_fmac_f32_e32 v20, v21, v20
	v_div_scale_f32 v21, vcc, v16, v5, v16
	v_mul_f32_e32 v24, v21, v20
	v_fma_f32 v25, -v17, v24, v21
	v_fmac_f32_e32 v24, v25, v20
	v_fma_f32 v17, -v17, v24, v21
	v_div_fmas_f32 v17, v17, v20, v24
	v_div_fixup_f32 v16, v17, v5, v16
	ds_write_b32 v23, v16 offset:128
	v_fma_f32 v16, v2, v26, v18
	v_div_scale_f32 v17, s[4:5], v6, v6, v16
	v_rcp_f32_e32 v18, v17
	s_nop 0
	v_fma_f32 v20, -v17, v18, 1.0
	v_fmac_f32_e32 v18, v20, v18
	v_div_scale_f32 v20, vcc, v16, v6, v16
	v_mul_f32_e32 v21, v20, v18
	v_fma_f32 v23, -v17, v21, v20
	v_fmac_f32_e32 v21, v23, v18
	v_fma_f32 v17, -v17, v21, v20
	v_div_fmas_f32 v17, v17, v18, v21
	v_div_fixup_f32 v16, v17, v6, v16
	ds_write_b32 v37, v16 offset:128
	v_div_scale_f32 v16, s[4:5], v7, v7, v19
	v_rcp_f32_e32 v17, v16
	s_nop 0
	v_fma_f32 v18, -v16, v17, 1.0
	v_fmac_f32_e32 v17, v18, v17
	v_div_scale_f32 v18, vcc, v19, v7, v19
	v_mul_f32_e32 v20, v18, v17
	v_fma_f32 v21, -v16, v20, v18
	v_fmac_f32_e32 v20, v21, v17
	v_fma_f32 v16, -v16, v20, v18
	v_div_fmas_f32 v16, v16, v17, v20
	v_div_fixup_f32 v16, v16, v7, v19
	ds_write_b32 v38, v16 offset:128
	v_lshl_add_u32 v8, s2, 2, v12
	s_lshl_b32 s2, s3, 3
	s_waitcnt lgkmcnt(0)
	v_mfma_f32_16x16x32_bf16 v[16:19], v[100:103], v[120:123], 0
	v_mfma_f32_16x16x32_bf16 v[24:27], v[108:111], v[128:131], 0
	v_mfma_f32_16x16x32_bf16 v[16:19], v[104:107], v[124:127], v[16:19]
	v_mfma_f32_16x16x32_bf16 v[24:27], v[112:115], v[132:135], v[24:27]
	s_mulk_i32 s3, 0x1080
	s_nop 6
	v_fma_f32 v0, v0, v24, v16
	v_div_scale_f32 v9, s[4:5], v4, v4, v0
	v_rcp_f32_e32 v10, v9
	v_fmac_f32_e32 v19, v3, v27
	v_fma_f32 v12, -v9, v10, 1.0
	v_fmac_f32_e32 v10, v12, v10
	v_div_scale_f32 v12, vcc, v0, v4, v0
	v_mul_f32_e32 v16, v12, v10
	v_fma_f32 v20, -v9, v16, v12
	v_fmac_f32_e32 v16, v20, v10
	v_fma_f32 v9, -v9, v16, v12
	v_div_fmas_f32 v9, v9, v10, v16
	v_div_fixup_f32 v0, v9, v4, v0
	v_mad_u32_u24 v4, v11, s6, v8
	ds_write_b32 v4, v0
	v_fma_f32 v0, v1, v25, v17
	v_div_scale_f32 v1, s[4:5], v5, v5, v0
	v_rcp_f32_e32 v4, v1
	s_nop 0
	v_fma_f32 v9, -v1, v4, 1.0
	v_fmac_f32_e32 v4, v9, v4
	v_div_scale_f32 v9, vcc, v0, v5, v0
	v_mul_f32_e32 v10, v9, v4
	v_fma_f32 v11, -v1, v10, v9
	v_fmac_f32_e32 v10, v11, v4
	v_fma_f32 v1, -v1, v10, v9
	v_div_fmas_f32 v1, v1, v4, v10
	v_div_fixup_f32 v0, v1, v5, v0
	v_add_u32_e32 v1, v8, v13
	ds_write_b32 v1, v0
	v_fma_f32 v0, v2, v26, v18
	v_div_scale_f32 v1, s[4:5], v6, v6, v0
	v_rcp_f32_e32 v2, v1
	s_nop 0
	v_fma_f32 v4, -v1, v2, 1.0
	v_fmac_f32_e32 v2, v4, v2
	v_div_scale_f32 v4, vcc, v0, v6, v0
	v_mul_f32_e32 v5, v4, v2
	v_fma_f32 v9, -v1, v5, v4
	v_fmac_f32_e32 v5, v9, v2
	v_fma_f32 v1, -v1, v5, v4
	v_div_fmas_f32 v1, v1, v2, v5
	v_div_fixup_f32 v0, v1, v6, v0
	v_add_u32_e32 v1, v8, v14
	ds_write_b32 v1, v0
	v_div_scale_f32 v0, s[4:5], v7, v7, v19
	v_rcp_f32_e32 v1, v0
	s_nop 0
	v_fma_f32 v2, -v0, v1, 1.0
	v_fmac_f32_e32 v1, v2, v1
	v_div_scale_f32 v2, vcc, v19, v7, v19
	v_mul_f32_e32 v3, v2, v1
	v_fma_f32 v4, -v0, v3, v2
	v_fmac_f32_e32 v3, v4, v1
	v_fma_f32 v0, -v0, v3, v2
	v_lshlrev_b32_e32 v2, 3, v22
	v_div_fmas_f32 v0, v0, v1, v3
	v_add_u32_e32 v10, s7, v2
	v_div_fixup_f32 v0, v0, v7, v19
	v_add_u32_e32 v1, v8, v15
	v_add_u32_e32 v6, s3, v10
	ds_write_b32 v1, v0
	s_waitcnt lgkmcnt(0)
	s_barrier
	s_add_u32 s4, s34, s2
	s_addc_u32 s5, s35, 0
	s_lshl_b64 s[4:5], s[4:5], 11
	s_lshl_b32 s3, s12, 1
	v_lshl_or_b32 v3, v22, 2, s3
	ds_read_b64 v[48:49], v6
	ds_read_b64 v[50:51], v6 offset:528
	ds_read_b64 v[52:53], v6 offset:1056
	ds_read_b64 v[54:55], v6 offset:1584
	ds_read_b64 v[56:57], v6 offset:2112
	ds_read_b64 v[58:59], v6 offset:2640
	ds_read_b64 v[60:61], v6 offset:3168
	ds_read_b64 v[62:63], v6 offset:3696
	s_add_u32 s98, s24, s4
	s_addc_u32 s99, s25, s5
	v_lshlrev_b32_e32 v90, 2, v201
	v_xor_b32_e32 v91, 4, v90
	v_xor_b32_e32 v92, 8, v90
	v_xor_b32_e32 v93, 16, v90
	v_xor_b32_e32 v94, 32, v90
	v_xor_b32_e32 v95, 64, v90
	v_xor_b32_e32 v96, 0x80, v90
	s_waitcnt lgkmcnt(0)
	v_pk_mul_f32 v[98:99], v[48:49], v[48:49]
	v_add_f32_e32 v64, v98, v99
	v_pk_mul_f32 v[98:99], v[50:51], v[50:51]
	v_add_f32_e32 v65, v98, v99
	v_pk_mul_f32 v[98:99], v[52:53], v[52:53]
	v_add_f32_e32 v66, v98, v99
	v_pk_mul_f32 v[98:99], v[54:55], v[54:55]
	v_add_f32_e32 v67, v98, v99
	v_pk_mul_f32 v[98:99], v[56:57], v[56:57]
	v_add_f32_e32 v68, v98, v99
	v_pk_mul_f32 v[98:99], v[58:59], v[58:59]
	v_add_f32_e32 v69, v98, v99
	v_pk_mul_f32 v[98:99], v[60:61], v[60:61]
	v_add_f32_e32 v70, v98, v99
	v_pk_mul_f32 v[98:99], v[62:63], v[62:63]
	v_add_f32_e32 v71, v98, v99
	ds_bpermute_b32 v72, v91, v64
	ds_bpermute_b32 v73, v91, v65
	ds_bpermute_b32 v74, v91, v66
	ds_bpermute_b32 v75, v91, v67
	ds_bpermute_b32 v76, v91, v68
	ds_bpermute_b32 v77, v91, v69
	ds_bpermute_b32 v78, v91, v70
	ds_bpermute_b32 v79, v91, v71
	s_waitcnt lgkmcnt(0)
	v_add_f32_e32 v64, v64, v72
	v_add_f32_e32 v65, v65, v73
	v_add_f32_e32 v66, v66, v74
	v_add_f32_e32 v67, v67, v75
	v_add_f32_e32 v68, v68, v76
	v_add_f32_e32 v69, v69, v77
	v_add_f32_e32 v70, v70, v78
	v_add_f32_e32 v71, v71, v79
	ds_bpermute_b32 v72, v92, v64
	ds_bpermute_b32 v73, v92, v65
	ds_bpermute_b32 v74, v92, v66
	ds_bpermute_b32 v75, v92, v67
	ds_bpermute_b32 v76, v92, v68
	ds_bpermute_b32 v77, v92, v69
	ds_bpermute_b32 v78, v92, v70
	ds_bpermute_b32 v79, v92, v71
	s_waitcnt lgkmcnt(0)
	v_add_f32_e32 v64, v64, v72
	v_add_f32_e32 v65, v65, v73
	v_add_f32_e32 v66, v66, v74
	v_add_f32_e32 v67, v67, v75
	v_add_f32_e32 v68, v68, v76
	v_add_f32_e32 v69, v69, v77
	v_add_f32_e32 v70, v70, v78
	v_add_f32_e32 v71, v71, v79
	ds_bpermute_b32 v72, v93, v64
	ds_bpermute_b32 v73, v93, v65
	ds_bpermute_b32 v74, v93, v66
	ds_bpermute_b32 v75, v93, v67
	ds_bpermute_b32 v76, v93, v68
	ds_bpermute_b32 v77, v93, v69
	ds_bpermute_b32 v78, v93, v70
	ds_bpermute_b32 v79, v93, v71
	s_waitcnt lgkmcnt(0)
	v_add_f32_e32 v64, v64, v72
	v_add_f32_e32 v65, v65, v73
	v_add_f32_e32 v66, v66, v74
	v_add_f32_e32 v67, v67, v75
	v_add_f32_e32 v68, v68, v76
	v_add_f32_e32 v69, v69, v77
	v_add_f32_e32 v70, v70, v78
	v_add_f32_e32 v71, v71, v79
	ds_bpermute_b32 v72, v94, v64
	ds_bpermute_b32 v73, v94, v65
	ds_bpermute_b32 v74, v94, v66
	ds_bpermute_b32 v75, v94, v67
	ds_bpermute_b32 v76, v94, v68
	ds_bpermute_b32 v77, v94, v69
	ds_bpermute_b32 v78, v94, v70
	ds_bpermute_b32 v79, v94, v71
	s_waitcnt lgkmcnt(0)
	v_add_f32_e32 v64, v64, v72
	v_add_f32_e32 v65, v65, v73
	v_add_f32_e32 v66, v66, v74
	v_add_f32_e32 v67, v67, v75
	v_add_f32_e32 v68, v68, v76
	v_add_f32_e32 v69, v69, v77
	v_add_f32_e32 v70, v70, v78
	v_add_f32_e32 v71, v71, v79
	ds_bpermute_b32 v72, v95, v64
	ds_bpermute_b32 v73, v95, v65
	ds_bpermute_b32 v74, v95, v66
	ds_bpermute_b32 v75, v95, v67
	ds_bpermute_b32 v76, v95, v68
	ds_bpermute_b32 v77, v95, v69
	ds_bpermute_b32 v78, v95, v70
	ds_bpermute_b32 v79, v95, v71
	s_waitcnt lgkmcnt(0)
	v_add_f32_e32 v64, v64, v72
	v_add_f32_e32 v65, v65, v73
	v_add_f32_e32 v66, v66, v74
	v_add_f32_e32 v67, v67, v75
	v_add_f32_e32 v68, v68, v76
	v_add_f32_e32 v69, v69, v77
	v_add_f32_e32 v70, v70, v78
	v_add_f32_e32 v71, v71, v79
	ds_bpermute_b32 v72, v96, v64
	ds_bpermute_b32 v73, v96, v65
	ds_bpermute_b32 v74, v96, v66
	ds_bpermute_b32 v75, v96, v67
	ds_bpermute_b32 v76, v96, v68
	ds_bpermute_b32 v77, v96, v69
	ds_bpermute_b32 v78, v96, v70
	ds_bpermute_b32 v79, v96, v71
	s_waitcnt lgkmcnt(0)
	v_add_f32_e32 v64, v64, v72
	v_add_f32_e32 v65, v65, v73
	v_add_f32_e32 v66, v66, v74
	v_add_f32_e32 v67, v67, v75
	v_add_f32_e32 v68, v68, v76
	v_add_f32_e32 v69, v69, v77
	v_add_f32_e32 v70, v70, v78
	v_add_f32_e32 v71, v71, v79
	v_fmamk_f32 v64, v64, 0x3c000000, v195
	v_cmp_gt_f32_e32 vcc, s67, v64
	v_mul_f32_e32 v72, 0x4b800000, v64
	s_nop 0
	v_cndmask_b32_e32 v64, v64, v72, vcc
	v_rsq_f32_e32 v64, v64
	s_nop 0
	v_mul_f32_e32 v72, 0x45800000, v64
	v_cndmask_b32_e32 v64, v64, v72, vcc
	v_fmamk_f32 v65, v65, 0x3c000000, v195
	v_cmp_gt_f32_e32 vcc, s67, v65
	v_mul_f32_e32 v73, 0x4b800000, v65
	s_nop 0
	v_cndmask_b32_e32 v65, v65, v73, vcc
	v_rsq_f32_e32 v65, v65
	s_nop 0
	v_mul_f32_e32 v73, 0x45800000, v65
	v_cndmask_b32_e32 v65, v65, v73, vcc
	v_fmamk_f32 v66, v66, 0x3c000000, v195
	v_cmp_gt_f32_e32 vcc, s67, v66
	v_mul_f32_e32 v74, 0x4b800000, v66
	s_nop 0
	v_cndmask_b32_e32 v66, v66, v74, vcc
	v_rsq_f32_e32 v66, v66
	s_nop 0
	v_mul_f32_e32 v74, 0x45800000, v66
	v_cndmask_b32_e32 v66, v66, v74, vcc
	v_fmamk_f32 v67, v67, 0x3c000000, v195
	v_cmp_gt_f32_e32 vcc, s67, v67
	v_mul_f32_e32 v75, 0x4b800000, v67
	s_nop 0
	v_cndmask_b32_e32 v67, v67, v75, vcc
	v_rsq_f32_e32 v67, v67
	s_nop 0
	v_mul_f32_e32 v75, 0x45800000, v67
	v_cndmask_b32_e32 v67, v67, v75, vcc
	v_fmamk_f32 v68, v68, 0x3c000000, v195
	v_cmp_gt_f32_e32 vcc, s67, v68
	v_mul_f32_e32 v76, 0x4b800000, v68
	s_nop 0
	v_cndmask_b32_e32 v68, v68, v76, vcc
	v_rsq_f32_e32 v68, v68
	s_nop 0
	v_mul_f32_e32 v76, 0x45800000, v68
	v_cndmask_b32_e32 v68, v68, v76, vcc
	v_fmamk_f32 v69, v69, 0x3c000000, v195
	v_cmp_gt_f32_e32 vcc, s67, v69
	v_mul_f32_e32 v77, 0x4b800000, v69
	s_nop 0
	v_cndmask_b32_e32 v69, v69, v77, vcc
	v_rsq_f32_e32 v69, v69
	s_nop 0
	v_mul_f32_e32 v77, 0x45800000, v69
	v_cndmask_b32_e32 v69, v69, v77, vcc
	v_fmamk_f32 v70, v70, 0x3c000000, v195
	v_cmp_gt_f32_e32 vcc, s67, v70
	v_mul_f32_e32 v78, 0x4b800000, v70
	s_nop 0
	v_cndmask_b32_e32 v70, v70, v78, vcc
	v_rsq_f32_e32 v70, v70
	s_nop 0
	v_mul_f32_e32 v78, 0x45800000, v70
	v_cndmask_b32_e32 v70, v70, v78, vcc
	v_fmamk_f32 v71, v71, 0x3c000000, v195
	v_cmp_gt_f32_e32 vcc, s67, v71
	v_mul_f32_e32 v79, 0x4b800000, v71
	s_nop 0
	v_cndmask_b32_e32 v71, v71, v79, vcc
	v_rsq_f32_e32 v71, v71
	s_nop 0
	v_mul_f32_e32 v79, 0x45800000, v71
	v_cndmask_b32_e32 v71, v71, v79, vcc
	s_waitcnt vmcnt(0)
	v_mul_f32_e32 v48, v48, v64
	v_mul_f32_e32 v49, v49, v64
	v_pk_mul_f32 v[48:49], v[234:235], v[48:49]
	v_lshlrev_b32_e32 v72, 16, v224
	v_and_b32_e32 v224, 0xffff0000, v224
	v_mul_f32_e32 v48, v48, v72
	v_mul_f32_e32 v49, v49, v224
	v_cvt_pk_bf16_f32 v72, v48, v49
	global_store_dword v3, v72, s[98:99]
	v_mul_f32_e32 v50, v50, v65
	v_mul_f32_e32 v51, v51, v65
	v_pk_mul_f32 v[50:51], v[234:235], v[50:51]
	v_lshlrev_b32_e32 v73, 16, v225
	v_and_b32_e32 v225, 0xffff0000, v225
	v_mul_f32_e32 v50, v50, v73
	v_mul_f32_e32 v51, v51, v225
	v_cvt_pk_bf16_f32 v73, v50, v51
	global_store_dword v3, v73, s[98:99] offset:2048
	s_add_u32 s98, s98, 0x1000
	s_addc_u32 s99, s99, 0
	v_mul_f32_e32 v52, v52, v66
	v_mul_f32_e32 v53, v53, v66
	v_pk_mul_f32 v[52:53], v[234:235], v[52:53]
	v_lshlrev_b32_e32 v74, 16, v226
	v_and_b32_e32 v226, 0xffff0000, v226
	v_mul_f32_e32 v52, v52, v74
	v_mul_f32_e32 v53, v53, v226
	v_cvt_pk_bf16_f32 v74, v52, v53
	global_store_dword v3, v74, s[98:99]
	v_mul_f32_e32 v54, v54, v67
	v_mul_f32_e32 v55, v55, v67
	v_pk_mul_f32 v[54:55], v[234:235], v[54:55]
	v_lshlrev_b32_e32 v75, 16, v227
	v_and_b32_e32 v227, 0xffff0000, v227
	v_mul_f32_e32 v54, v54, v75
	v_mul_f32_e32 v55, v55, v227
	v_cvt_pk_bf16_f32 v75, v54, v55
	global_store_dword v3, v75, s[98:99] offset:2048
	s_add_u32 s98, s98, 0x1000
	s_addc_u32 s99, s99, 0
	v_mul_f32_e32 v56, v56, v68
	v_mul_f32_e32 v57, v57, v68
	v_pk_mul_f32 v[56:57], v[234:235], v[56:57]
	v_lshlrev_b32_e32 v76, 16, v228
	v_and_b32_e32 v228, 0xffff0000, v228
	v_mul_f32_e32 v56, v56, v76
	v_mul_f32_e32 v57, v57, v228
	v_cvt_pk_bf16_f32 v76, v56, v57
	global_store_dword v3, v76, s[98:99]
	v_mul_f32_e32 v58, v58, v69
	v_mul_f32_e32 v59, v59, v69
	v_pk_mul_f32 v[58:59], v[234:235], v[58:59]
	v_lshlrev_b32_e32 v77, 16, v229
	v_and_b32_e32 v229, 0xffff0000, v229
	v_mul_f32_e32 v58, v58, v77
	v_mul_f32_e32 v59, v59, v229
	v_cvt_pk_bf16_f32 v77, v58, v59
	global_store_dword v3, v77, s[98:99] offset:2048
	s_add_u32 s98, s98, 0x1000
	s_addc_u32 s99, s99, 0
	v_mul_f32_e32 v60, v60, v70
	v_mul_f32_e32 v61, v61, v70
	v_pk_mul_f32 v[60:61], v[234:235], v[60:61]
	v_lshlrev_b32_e32 v78, 16, v230
	v_and_b32_e32 v230, 0xffff0000, v230
	v_mul_f32_e32 v60, v60, v78
	v_mul_f32_e32 v61, v61, v230
	v_cvt_pk_bf16_f32 v78, v60, v61
	global_store_dword v3, v78, s[98:99]
	v_mul_f32_e32 v62, v62, v71
	v_mul_f32_e32 v63, v63, v71
	v_pk_mul_f32 v[62:63], v[234:235], v[62:63]
	v_lshlrev_b32_e32 v79, 16, v231
	v_and_b32_e32 v231, 0xffff0000, v231
	v_mul_f32_e32 v62, v62, v79
	v_mul_f32_e32 v63, v63, v231
	v_cvt_pk_bf16_f32 v79, v62, v63
	global_store_dword v3, v79, s[98:99] offset:2048
	s_add_i32 s39, s39, s71
	s_cmpk_gt_i32 s39, 0x7ff
	s_barrier
	s_cbranch_scc1 .LBB0_494
